# combined: dil attention 3-stage staging, QKV epilogue prefetch, transposes gain-load hoist, MLA packed row-sum adds, nt SwiGLU stores, on top of final-norm pipelining
# baseline (speedup 1.0000x reference)
.LBB0_31:
	s_lshr_b32 s15, s42, 5
	v_cvt_f32_u32_e32 v2, s15
	s_and_b32 s12, s43, 0xffff
	v_cvt_f32_u32_e32 v3, s12
	v_mov_b32_e32 v38, 1.0
	v_rcp_iflag_f32_e32 v4, v2
	v_mov_b32_e32 v40, 1.0
	v_mul_f32_e32 v4, v3, v4
	v_trunc_f32_e32 v4, v4
	v_cvt_u32_f32_e32 v5, v4
	v_fma_f32 v3, -v4, v2, v3
	v_cmp_ge_f32_e64 s[12:13], |v3|, v2
	s_cmp_lg_u64 s[12:13], 0
	v_readfirstlane_b32 s12, v5
	s_addc_u32 s12, s12, 0
	s_and_b32 s13, s12, 0xffff
	s_mul_i32 s12, s12, s15
	s_sub_i32 s49, s43, s12
	s_lshl_b32 s12, s49, 7
	s_lshl_b32 s48, s13, 6
	s_and_b32 s12, s12, 0x3ff80
	v_or_b32_e32 v47, s48, v39
	s_add_u32 s2, s2, s12
	s_addc_u32 s3, s3, 0
	v_or_b32_e32 v6, 8, v47
	v_mul_hi_u32_u24_e32 v3, s42, v47
	v_lshl_add_u64 v[4:5], s[2:3], 0, v[36:37]
	v_mul_u32_u24_e32 v2, s42, v47
	v_mul_hi_u32_u24_e32 v7, s42, v6
	v_mul_u32_u24_e32 v6, s42, v6
	v_lshl_add_u64 v[2:3], v[2:3], 2, v[4:5]
	v_lshl_add_u64 v[6:7], v[6:7], 2, v[4:5]
	global_load_dwordx4 v[30:33], v[2:3], off
	global_load_dwordx4 v[26:29], v[6:7], off
	v_or_b32_e32 v2, 16, v47
	v_or_b32_e32 v6, 24, v47
	v_mul_hi_u32_u24_e32 v3, s42, v2
	v_mul_u32_u24_e32 v2, s42, v2
	v_mul_hi_u32_u24_e32 v7, s42, v6
	v_mul_u32_u24_e32 v6, s42, v6
	v_lshl_add_u64 v[2:3], v[2:3], 2, v[4:5]
	v_lshl_add_u64 v[6:7], v[6:7], 2, v[4:5]
	global_load_dwordx4 v[22:25], v[2:3], off
	global_load_dwordx4 v[18:21], v[6:7], off
	v_or_b32_e32 v2, 32, v47
	v_or_b32_e32 v6, 40, v47
	v_mul_hi_u32_u24_e32 v3, s42, v2
	v_mul_u32_u24_e32 v2, s42, v2
	v_mul_hi_u32_u24_e32 v7, s42, v6
	v_mul_u32_u24_e32 v6, s42, v6
	v_lshl_add_u64 v[2:3], v[2:3], 2, v[4:5]
	v_lshl_add_u64 v[6:7], v[6:7], 2, v[4:5]
	global_load_dwordx4 v[14:17], v[2:3], off
	global_load_dwordx4 v[10:13], v[6:7], off
	v_or_b32_e32 v2, 48, v47
	v_or_b32_e32 v6, 56, v47
	v_mul_hi_u32_u24_e32 v3, s42, v2
	v_mul_u32_u24_e32 v2, s42, v2
	v_mul_hi_u32_u24_e32 v7, s42, v6
	v_mul_u32_u24_e32 v6, s42, v6
	v_lshl_add_u64 v[2:3], v[2:3], 2, v[4:5]
	v_lshl_add_u64 v[4:5], v[6:7], 2, v[4:5]
	global_load_dwordx4 v[6:9], v[2:3], off
	s_nop 0
	global_load_dwordx4 v[2:5], v[4:5], off
	v_add_lshl_u32 v46, s48, v39, 2
	v_mov_b32_e32 v50, 1.0
	v_mov_b32_e32 v52, 1.0
	v_mov_b32_e32 v54, 1.0
	v_mov_b32_e32 v56, 1.0
	v_mov_b32_e32 v58, 1.0
	v_mov_b32_e32 v60, 1.0
	v_mov_b32_e32 v62, 1.0
	v_mov_b32_e32 v64, 1.0
	s_cmp_lg_u64 s[38:39], 0
	s_cbranch_scc0 .Lt_nog
	v_lshlrev_b32_e32 v40, 2, v47
	global_load_dword v50, v40, s[38:39]
	global_load_dword v52, v46, s[38:39] offset:32
	global_load_dword v54, v46, s[38:39] offset:64
	global_load_dword v56, v46, s[38:39] offset:96
	global_load_dword v58, v46, s[38:39] offset:128
	global_load_dword v60, v46, s[38:39] offset:160
	global_load_dword v62, v46, s[38:39] offset:192
	global_load_dword v64, v46, s[38:39] offset:224
.Lt_nog:
	s_waitcnt vmcnt(0)
	v_pk_mul_f32 v[30:31], v[30:31], v[50:51] op_sel_hi:[1,0]
	v_pk_mul_f32 v[32:33], v[32:33], v[50:51] op_sel_hi:[1,0]
	ds_write2_b32 v45, v30, v31 offset1:1
	ds_write2_b32 v45, v32, v33 offset0:2 offset1:3
	v_pk_mul_f32 v[26:27], v[26:27], v[52:53] op_sel_hi:[1,0]
	v_pk_mul_f32 v[28:29], v[28:29], v[52:53] op_sel_hi:[1,0]
	v_add_u32_e32 v66, 0x420, v45
	ds_write2_b32 v66, v26, v27 offset1:1
	ds_write2_b32 v66, v28, v29 offset0:2 offset1:3
	v_pk_mul_f32 v[22:23], v[22:23], v[54:55] op_sel_hi:[1,0]
	v_pk_mul_f32 v[24:25], v[24:25], v[54:55] op_sel_hi:[1,0]
	v_add_u32_e32 v66, 0x840, v45
	ds_write2_b32 v66, v22, v23 offset1:1
	ds_write2_b32 v66, v24, v25 offset0:2 offset1:3
	v_pk_mul_f32 v[18:19], v[18:19], v[56:57] op_sel_hi:[1,0]
	v_pk_mul_f32 v[20:21], v[20:21], v[56:57] op_sel_hi:[1,0]
	v_add_u32_e32 v66, 0xc60, v45
	ds_write2_b32 v66, v18, v19 offset1:1
	ds_write2_b32 v66, v20, v21 offset0:2 offset1:3
	v_pk_mul_f32 v[14:15], v[14:15], v[58:59] op_sel_hi:[1,0]
	v_pk_mul_f32 v[16:17], v[16:17], v[58:59] op_sel_hi:[1,0]
	v_add_u32_e32 v66, 0x1080, v45
	ds_write2_b32 v66, v14, v15 offset1:1
	ds_write2_b32 v66, v16, v17 offset0:2 offset1:3
	v_pk_mul_f32 v[10:11], v[10:11], v[60:61] op_sel_hi:[1,0]
	v_pk_mul_f32 v[12:13], v[12:13], v[60:61] op_sel_hi:[1,0]
	v_add_u32_e32 v66, 0x14a0, v45
	ds_write2_b32 v66, v10, v11 offset1:1
	ds_write2_b32 v66, v12, v13 offset0:2 offset1:3
	v_pk_mul_f32 v[6:7], v[6:7], v[62:63] op_sel_hi:[1,0]
	v_pk_mul_f32 v[8:9], v[8:9], v[62:63] op_sel_hi:[1,0]
	v_add_u32_e32 v66, 0x18c0, v45
	ds_write2_b32 v66, v6, v7 offset1:1
	ds_write2_b32 v66, v8, v9 offset0:2 offset1:3
	v_pk_mul_f32 v[2:3], v[2:3], v[64:65] op_sel_hi:[1,0]
	v_pk_mul_f32 v[4:5], v[4:5], v[64:65] op_sel_hi:[1,0]
	v_add_u32_e32 v66, 0x1ce0, v45
	ds_write2_b32 v66, v2, v3 offset1:1
	ds_write2_b32 v66, v4, v5 offset0:2 offset1:3
	s_lshl_b32 s2, s49, 5
	s_waitcnt lgkmcnt(0)
	s_and_b32 s2, 0xffff, s2
	s_cmp_eq_u32 s47, 0
	s_cbranch_scc1 .LBB0_9
	s_and_b32 s3, 0xffff, s49
	s_add_i32 s12, s2, 0xfffff500
	s_cmpk_lt_u32 s3, 0x58
	s_cselect_b32 s2, s2, s12
	s_sext_i32_i16 s12, s2
	s_cselect_b32 s3, 0, 0x80
	s_bfe_u32 s12, s12, 0x70018
	s_add_i32 s3, s2, s3
	s_add_i32 s2, s2, s12
	s_sext_i32_i16 s2, s2
	s_and_b32 s2, s2, 0xffffff80
	s_add_i32 s2, s3, s2
	s_branch .LBB0_9
